# attention loop: K row pointer kept and incremented, LDS addresses pre-combined (10 fewer VALU per tile); scan loop placed +40 bytes
# speedup vs baseline: 1.0029x; 1.0001x over previous
; DEVI float shfl_xor_(float v, int o) { return __int_as_float(__builtin_amdgcn_ds_bpermute((lane_id_() ^ o) << 2, __float_as_int(v))); }
; template <bool SHIFT> DEVI void attn_body(const Params& p, int l, int idx, unsigned char* smem, float lam, float lam_init) {
;     ...
;     const bf16_t* qp = QK + (size_t)(qrow0 + wave * 32 + r32) * 1024 + h * 64 + hh * 8;
; #pragma unroll
;     for (int s = 0; s < 2; ++s)
; #pragma unroll
;       for (int ks = 0; ks < 2; ++ks) qf[s][ks] = *(const bf16x8*)(qp + s * 32 + ks * 16);
;   }
;   const int lkey = tid >> 2, lc0 = (tid & 3) * 2;
;   u32x4 rk0, rk1, rv0, rv1;
;     ...
;   f32x16 O[2][2];
; #pragma unroll
;   for (int s = 0; s < 2; ++s)
; #pragma unroll
;     for (int d = 0; d < 2; ++d)
; #pragma unroll
;       for (int e = 0; e < 16; ++e) O[s][d][e] = 0.f;
;   float mref[2];
;   f32x2 lacc[2];
;   int need = 0;
;   {
;     const float* KM = (const float*)(p.ws + OFF_KM);
; #pragma unroll
;     for (int s = 0; s < 2; ++s) {
;       float ss = 0.f;
; #pragma unroll
;       for (int ks = 0; ks < 2; ++ks)
; #pragma unroll
;         for (int j = 0; j < 8; ++j) { const float v = __uint_as_float(((unsigned)(unsigned short)qf[s][ks][j]) << 16); ss += v * v; }
;       ss += shfl_xor_(ss, 32);
;       mref[s] = sqrtf(ss * KM[(b * 8 + h) * 2 + s]);
;       need |= (mref[s] > 96.0f) ? 1 : 0;
;       lacc[s] = (f32x2){0.f, 0.f};
;     }
;   }
;   (void)need;
;   const f32x16 zero16 = {0.f, 0.f, 0.f, 0.f, 0.f, 0.f, 0.f, 0.f, 0.f, 0.f, 0.f, 0.f, 0.f, 0.f, 0.f, 0.f};
;   AT_LOAD(kt0);
;   AT_STORE(0);
;   __syncthreads();
.LBB0_165:
	s_and_b32 s22, s37, s24
	v_ashrrev_i32_e32 v0, 1, v2
	s_movk_i32 s23, 0xffe0
	v_bfi_b32 v0, s23, v0, v2
	s_add_i32 s22, s36, s22
	v_add_u32_e32 v0, s22, v0
	v_ashrrev_i32_e32 v1, 31, v0
	v_readlane_b32 s36, v252, 4
	s_and_b32 s27, s27, 7
	v_lshlrev_b64 v[0:1], 11, v[0:1]
	v_readlane_b32 s50, v252, 18
	v_readlane_b32 s51, v252, 19
	v_bfe_u32 v3, v2, 5, 1
	s_lshl_b32 s96, s27, 7
	v_lshl_add_u64 v[174:175], s[50:51], 0, v[0:1]
	v_lshl_add_u64 v[0:1], v[174:175], 0, s[96:97]
	v_lshlrev_b32_e32 v162, 4, v3
	v_lshl_add_u64 v[0:1], v[0:1], 0, v[162:163]
	global_load_dwordx4 v[96:99], v[0:1], off
	global_load_dwordx4 v[100:103], v[0:1], off offset:32
	global_load_dwordx4 v[104:107], v[0:1], off offset:64
	global_load_dwordx4 v[108:111], v[0:1], off offset:96
	v_mov_b32_e32 v0, v225
	v_ashrrev_i32_e32 v14, 2, v2
	s_lshl_b32 s24, s25, 6
	v_mov_b32_e32 v0, v225
	v_add_u32_e32 v1, s24, v14
	s_movk_i32 s22, 0x1fff
	v_cmp_lt_i32_e32 vcc, s22, v1
	v_readlane_b32 s37, v252, 5
	v_readlane_b32 s38, v252, 6
	v_readlane_b32 s39, v252, 7
	v_readlane_b32 s40, v252, 8
	v_readlane_b32 s41, v252, 9
	v_readlane_b32 s42, v252, 10
	v_readlane_b32 s43, v252, 11
	v_readlane_b32 s44, v252, 12
	v_readlane_b32 s45, v252, 13
	v_readlane_b32 s46, v252, 14
	v_readlane_b32 s47, v252, 15
	v_readlane_b32 s48, v252, 16
	v_readlane_b32 s49, v252, 17
	s_and_saveexec_b64 s[22:23], vcc
	s_xor_b64 s[22:23], exec, s[22:23]
	s_lshl_b32 s31, s26, 8
	v_add_u32_e32 v0, s31, v1
	s_lshl_b32 s36, s26, 13
	v_add_u32_e32 v0, 0x6000, v0
	v_mov_b32_e32 v170, s36
	v_mov_b32_e32 v4, s31
	s_or_saveexec_b64 s[22:23], s[22:23]
	v_readlane_b32 s38, v253, 18
	v_readlane_b32 s39, v253, 19
	s_xor_b64 exec, exec, s[22:23]
	s_lshl_b32 s31, s26, 13
	s_lshl_b32 s36, s26, 8
	v_add_u32_e32 v0, s31, v1
	v_mov_b32_e32 v170, s31
	v_mov_b32_e32 v4, s36
	s_or_b64 exec, exec, s[22:23]
	s_lshl_b32 s22, s26, 3
	s_or_b32 s22, s22, s27
	s_lshl_b32 s31, s27, 6
	s_mul_i32 s27, s22, 0x108000
	s_mul_hi_u32 s26, s22, 0x108000
	s_add_u32 s22, s38, s27
	s_addc_u32 s23, s39, s26
	v_ashrrev_i32_e32 v1, 31, v0
	v_readlane_b32 s36, v252, 4
	v_lshlrev_b32_e32 v5, 1, v2
	v_lshlrev_b64 v[0:1], 11, v[0:1]
	v_readlane_b32 s50, v252, 18
	v_readlane_b32 s51, v252, 19
	v_and_b32_e32 v15, 6, v5
	s_lshl_b32 s96, s31, 1
	v_lshl_add_u64 v[0:1], s[50:51], 0, v[0:1]
	v_lshl_add_u64 v[0:1], v[0:1], 0, s[96:97]
	v_lshlrev_b32_e32 v16, 4, v15
	v_mov_b32_e32 v17, v163
	v_lshl_add_u64 v[0:1], v[0:1], 0, v[16:17]
	global_load_dwordx4 v[112:115], v[0:1], off offset:1040
	global_load_dwordx4 v[116:119], v[0:1], off offset:1024
	v_mov_b64_e32 v[0:1], s[22:23]
	s_movk_i32 s31, 0x4200
	v_mad_i64_i32 v[0:1], s[22:23], v14, s31, v[0:1]
	s_lshl_b32 s22, s24, 1
	s_mov_b32 s23, s97
	v_lshl_add_u64 v[0:1], v[0:1], 0, s[22:23]
	v_lshl_add_u64 v[0:1], v[0:1], 0, v[16:17]
	global_load_dwordx4 v[120:123], v[0:1], off
	global_load_dwordx4 v[124:127], v[0:1], off offset:16
	v_and_b32_e32 v1, 31, v2
	v_lshlrev_b32_e32 v172, 3, v3
	s_movk_i32 s22, 0x88
	v_mad_u32_u24 v242, v1, s22, v172
	s_add_u32 s22, s50, s96
	v_add3_u32 v240, v14, s24, 64
	s_addc_u32 s23, s51, 0
	s_add_i32 s24, s25, -1
	s_lshl_b32 s25, s25, 7
	v_lshlrev_b32_e32 v173, 7, v14
	v_bfe_u32 v18, v2, 3, 3
	v_lshlrev_b32_e32 v19, 3, v14
	v_lshl_add_u64 v[176:177], s[22:23], 0, v[16:17]
	s_or_b32 s22, s27, s25
	v_bitop3_b32 v21, v5, v18, 6 bitop3:0x6c
	v_bitop3_b32 v15, v15, v18, 1 bitop3:0x36
	v_add3_u32 v249, v173, v19, v16
	v_mov_b32_e32 v19, s26
	v_mov_b32_e32 v18, s22
	v_lshrrev_b32_e32 v6, 1, v2
	v_bfe_u32 v7, v2, 1, 3
	v_lshlrev_b32_e32 v248, 4, v15
	v_mad_i64_i32 v[14:15], s[22:23], v14, s31, v[18:19]
	v_and_b32_e32 v20, 3, v2
	v_bitop3_b32 v22, v3, v6, 7 bitop3:0x78
	v_bitop3_b32 v23, v3, v7, 2 bitop3:0x36
	v_bitop3_b32 v24, v3, v7, 4 bitop3:0x36
	v_lshlrev_b32_e32 v243, 4, v21
	v_readlane_b32 s22, v255, 15
	v_mov_b32_e32 v0, 0
	v_bitop3_b32 v25, v3, v7, 6 bitop3:0x36
	v_lshlrev_b32_e32 v244, 4, v22
	v_lshlrev_b32_e32 v245, 4, v23
	v_lshlrev_b32_e32 v246, 4, v24
	v_or_b32_e32 v21, v173, v243
	v_or_b32_e32 v22, v173, v248
	v_add_u32_e32 v23, 0x4000, v249
	v_add_u32_e32 v24, 0x4010, v249
	v_lshl_or_b32 v14, v20, 5, v14
	v_readlane_b32 s23, v255, 16
	v_add_u32_e32 v239, 0x6000, v4
	v_lshlrev_b32_e32 v241, 7, v1
	v_mov_b32_e32 v1, v0
	v_mov_b32_e32 v2, v0
	v_mov_b32_e32 v3, v0
	v_mov_b32_e32 v4, v0
	v_mov_b32_e32 v5, v0
	v_mov_b32_e32 v6, v0
	v_mov_b32_e32 v7, v0
	v_mov_b32_e32 v8, v0
	v_mov_b32_e32 v9, v0
	v_mov_b32_e32 v10, v0
	v_mov_b32_e32 v11, v0
	v_mov_b32_e32 v12, v0
	v_mov_b32_e32 v13, v0
	v_lshlrev_b32_e32 v247, 4, v25
	v_lshl_add_u64 v[178:179], s[22:23], 0, v[14:15]
	v_mov_b32_e32 v14, v0
	v_mov_b32_e32 v15, v0
	v_mov_b32_e32 v32, v0
	v_mov_b32_e32 v33, v0
	v_mov_b32_e32 v34, v0
	v_mov_b32_e32 v35, v0
	s_waitcnt vmcnt(2)
	ds_write_b128 v21, v[116:119]
	ds_write_b128 v22, v[112:115]
	s_waitcnt vmcnt(1)
	ds_write2_b64 v23, v[120:121], v[122:123] offset1:1
	s_waitcnt vmcnt(0)
	ds_write2_b64 v24, v[124:125], v[126:127] offset1:1
	v_mov_b32_e32 v36, v0
	v_mov_b32_e32 v37, v0
	v_mov_b32_e32 v38, v0
	v_mov_b32_e32 v39, v0
	v_mov_b32_e32 v40, v0
	v_mov_b32_e32 v41, v0
	v_mov_b32_e32 v42, v0
	v_mov_b32_e32 v43, v0
	v_mov_b32_e32 v44, v0
	v_mov_b32_e32 v45, v0
	v_mov_b32_e32 v46, v0
	v_mov_b32_e32 v47, v0
	v_mov_b32_e32 v16, v0
	v_mov_b32_e32 v17, v0
	v_mov_b32_e32 v18, v0
	v_mov_b32_e32 v19, v0
	v_mov_b32_e32 v20, v0
	v_mov_b32_e32 v21, v0
	v_mov_b32_e32 v22, v0
	v_mov_b32_e32 v23, v0
	v_mov_b32_e32 v24, v0
	v_mov_b32_e32 v25, v0
	v_mov_b32_e32 v26, v0
	v_mov_b32_e32 v27, v0
	v_mov_b32_e32 v28, v0
	v_mov_b32_e32 v29, v0
	v_mov_b32_e32 v30, v0
	v_mov_b32_e32 v31, v0
	v_mov_b32_e32 v48, v0
	v_mov_b32_e32 v49, v0
	v_mov_b32_e32 v50, v0
	v_mov_b32_e32 v51, v0
	v_mov_b32_e32 v52, v0
	v_mov_b32_e32 v53, v0
	v_mov_b32_e32 v54, v0
	v_mov_b32_e32 v55, v0
	v_mov_b32_e32 v56, v0
	v_mov_b32_e32 v57, v0
	v_mov_b32_e32 v58, v0
	v_mov_b32_e32 v59, v0
	v_mov_b32_e32 v60, v0
	v_mov_b32_e32 v61, v0
	v_mov_b32_e32 v62, v0
	v_mov_b32_e32 v63, v0
	v_mov_b32_e32 v180, v0
	v_mov_b32_e32 v181, v0
	v_mov_b32_e32 v182, v0
	v_mov_b32_e32 v183, v0
	v_readlane_b32 s37, v252, 5
	v_readlane_b32 s38, v252, 6
	v_readlane_b32 s39, v252, 7
	v_readlane_b32 s40, v252, 8
	v_readlane_b32 s41, v252, 9
	v_readlane_b32 s42, v252, 10
	v_readlane_b32 s43, v252, 11
	v_readlane_b32 s44, v252, 12
	v_readlane_b32 s45, v252, 13
	v_readlane_b32 s46, v252, 14
	v_readlane_b32 s47, v252, 15
	v_readlane_b32 s48, v252, 16
	v_readlane_b32 s49, v252, 17
	s_waitcnt lgkmcnt(0)
	s_barrier
	v_add_u32_e32 v244, v241, v244
	v_add_u32_e32 v245, v241, v245
	v_add_u32_e32 v246, v241, v246
	v_add_u32_e32 v247, v241, v247
	v_add_u32_e32 v242, 0x4000, v242
	v_add_u32_e32 v243, v173, v243
	v_add_u32_e32 v248, v173, v248
	v_add_u32_e32 v249, 0x4000, v249
	v_cmp_gt_i32_e32 vcc, s2, v240
	s_nop 1
	v_cndmask_b32_e32 v250, v239, v170, vcc
	v_add_u32_e32 v250, v250, v240
	v_ashrrev_i32_e32 v251, 31, v250
	v_lshlrev_b64 v[250:251], 11, v[250:251]
	v_lshl_add_u64 v[250:251], v[176:177], 0, v[250:251]
	s_branch .LBB0_171

; template <bool SHIFT> DEVI void attn_body(const Params& p, int l, int idx, unsigned char* smem, float lam, float lam_init) {
;     ...
;   for (int kt = kt0; kt < kt1; ++kt) {
;     const int buf = (kt - kt0) & 1;
;     const bool more = (kt + 1 < kt1);
;     if (more) AT_LOAD(kt + 1);
;     const unsigned char* kb = KB + buf * AT_KB;
;     const unsigned char* vb = VB + buf * AT_VB;
;     ...
;     {
;       f32x16 scA, scB;
;       AT_QK(0, 0, scA);
;       AT_QK(0, 1, scB);
;       AT_SPV(0, 0, scA);
;       AT_QK(1, 0, scA);
;       AT_SPV(0, 1, scB);
;       AT_QK(1, 1, scB);
;       AT_SPV(1, 0, scA);
;       AT_SPV(1, 1, scB);
.LBB0_171:
	s_cmpk_lg_i32 s24, 0x82
	s_cselect_b64 s[22:23], -1, 0
	s_cmpk_eq_i32 s24, 0x82
	s_cbranch_scc1 .LBB0_173
	s_cmpk_lg_i32 s24, 0x7e
	s_cbranch_scc1 .Lkp_norm
	v_cmp_gt_i32_e32 vcc, s2, v240
	s_nop 1
	v_cndmask_b32_e32 v250, v239, v170, vcc
	v_add_u32_e32 v250, v250, v240
	v_ashrrev_i32_e32 v251, 31, v250
	v_lshlrev_b64 v[250:251], 11, v[250:251]
	v_lshl_add_u64 v[250:251], v[176:177], 0, v[250:251]
.Lkp_norm:
	s_mov_b32 s26, 0x20000
	s_mov_b32 s27, 0
	global_load_dwordx4 v[112:115], v[250:251], off offset:1040
	global_load_dwordx4 v[116:119], v[250:251], off offset:1024
	global_load_dwordx4 v[124:127], v[178:179], off offset:16
	global_load_dwordx4 v[120:123], v[178:179], off
	v_lshl_add_u64 v[250:251], v[250:251], 0, s[26:27]
.LBB0_173:
	s_add_i32 s24, s24, 1
	s_and_b32 s25, s24, 1
	v_lshl_add_u32 v68, s25, 13, v244
	ds_read_b128 v[64:67], v68
	v_lshl_add_u32 v136, s25, 13, v245
	ds_read_b128 v[132:135], v136
	s_mul_i32 s26, s25, 0x2200
	v_add_u32_e32 v137, s26, v242
	v_add_u32_e32 v138, 0x1000, v137
	ds_read2_b64 v[128:131], v137 offset1:2
	ds_read2_b64 v[152:155], v138 offset0:32 offset1:34
	s_waitcnt lgkmcnt(3)
	v_mfma_f32_32x32x16_bf16 v[80:95], v[64:67], v[96:99], 0
	ds_read2_b64 v[144:147], v137 offset0:4 offset1:6
	ds_read2_b64 v[156:159], v138 offset0:36 offset1:38
	ds_read_b128 v[64:67], v68 offset:4096
	ds_read2_b64 v[140:143], v137 offset0:8 offset1:10
	ds_read2_b64 v[148:151], v138 offset0:40 offset1:42
	v_lshl_add_u32 v217, s25, 13, v246
	v_lshl_add_u32 v220, s25, 13, v247
	s_waitcnt lgkmcnt(7)
	v_mfma_f32_32x32x16_bf16 v[80:95], v[132:135], v[100:103], v[80:95]
	ds_read2_b64 v[132:135], v137 offset0:12 offset1:14
	s_andn2_b64 vcc, exec, s[22:23]
	s_nop 9
	v_exp_f32_e32 v192, v80
	v_exp_f32_e32 v193, v81
	v_exp_f32_e32 v188, v82
	v_exp_f32_e32 v189, v83
	v_exp_f32_e32 v186, v84
	v_exp_f32_e32 v187, v85
	v_exp_f32_e32 v184, v86
	v_exp_f32_e32 v185, v87
	v_cvt_pk_bf16_f32 v80, v192, v193
	v_cvt_pk_bf16_f32 v81, v188, v189
	v_cvt_pk_bf16_f32 v82, v186, v187
	v_cvt_pk_bf16_f32 v83, v184, v185
	v_exp_f32_e32 v198, v88
	s_waitcnt lgkmcnt(7)
	v_mfma_f32_32x32x16_bf16 v[48:63], v[128:131], v[80:83], v[48:63]
	v_exp_f32_e32 v199, v89
	v_exp_f32_e32 v196, v90
	v_exp_f32_e32 v197, v91
	v_exp_f32_e32 v190, v92
	v_exp_f32_e32 v191, v93
	v_exp_f32_e32 v194, v94
	v_exp_f32_e32 v195, v95
	s_waitcnt lgkmcnt(6)
	v_mfma_f32_32x32x16_bf16 v[16:31], v[152:155], v[80:83], v[16:31]
	v_cvt_pk_bf16_f32 v80, v198, v199
	v_cvt_pk_bf16_f32 v81, v196, v197
	v_cvt_pk_bf16_f32 v82, v190, v191
	v_cvt_pk_bf16_f32 v83, v194, v195
	s_waitcnt lgkmcnt(5)
	v_mfma_f32_32x32x16_bf16 v[48:63], v[144:147], v[80:83], v[48:63]
	s_waitcnt lgkmcnt(4)
	v_mfma_f32_32x32x16_bf16 v[16:31], v[156:159], v[80:83], v[16:31]
	ds_read_b128 v[80:83], v136 offset:4096
	ds_read2_b64 v[136:139], v138 offset0:44 offset1:46
	s_waitcnt lgkmcnt(5)
	v_mfma_f32_32x32x16_bf16 v[64:79], v[64:67], v[96:99], 0
	s_waitcnt lgkmcnt(1)
	v_mfma_f32_32x32x16_bf16 v[64:79], v[80:83], v[100:103], v[64:79]
	ds_read_b128 v[80:83], v217
	v_add_f32_e32 v182, v182, v192
	v_add_f32_e32 v183, v183, v193
	v_add_f32_e32 v182, v182, v188
	v_add_f32_e32 v183, v183, v189
	v_add_f32_e32 v182, v182, v186
	v_add_f32_e32 v183, v183, v187
	v_add_f32_e32 v182, v182, v184
	v_add_f32_e32 v183, v183, v185
	v_add_f32_e32 v182, v182, v198
	v_add_f32_e32 v183, v183, v199
	v_add_f32_e32 v182, v182, v196
	v_add_f32_e32 v183, v183, v197
	v_add_f32_e32 v182, v182, v190
	v_add_f32_e32 v183, v183, v191
	v_add_f32_e32 v182, v182, v194
	v_add_f32_e32 v183, v183, v195
	v_exp_f32_e32 v204, v64
	v_exp_f32_e32 v205, v65
	v_exp_f32_e32 v202, v66
	v_exp_f32_e32 v203, v67
	v_exp_f32_e32 v200, v68
	v_exp_f32_e32 v201, v69
	v_exp_f32_e32 v206, v70
	v_exp_f32_e32 v207, v71
	v_cvt_pk_bf16_f32 v64, v204, v205
	v_cvt_pk_bf16_f32 v65, v202, v203
	v_cvt_pk_bf16_f32 v66, v200, v201
	v_cvt_pk_bf16_f32 v67, v206, v207
	v_exp_f32_e32 v214, v72
	v_mfma_f32_32x32x16_bf16 v[48:63], v[140:143], v[64:67], v[48:63]
	v_exp_f32_e32 v215, v73
	v_exp_f32_e32 v212, v74
	v_exp_f32_e32 v213, v75
	v_exp_f32_e32 v208, v76
	v_exp_f32_e32 v209, v77
	v_exp_f32_e32 v210, v78
	v_exp_f32_e32 v211, v79
	v_mfma_f32_32x32x16_bf16 v[16:31], v[148:151], v[64:67], v[16:31]
	v_cvt_pk_bf16_f32 v64, v214, v215
	v_cvt_pk_bf16_f32 v65, v212, v213
	v_cvt_pk_bf16_f32 v66, v208, v209
	v_cvt_pk_bf16_f32 v67, v210, v211
	s_nop 0
	v_mfma_f32_32x32x16_bf16 v[48:63], v[132:135], v[64:67], v[48:63]
	s_waitcnt lgkmcnt(1)
	v_mfma_f32_32x32x16_bf16 v[16:31], v[136:139], v[64:67], v[16:31]
	ds_read_b128 v[64:67], v220
	s_waitcnt lgkmcnt(1)
	v_mfma_f32_32x32x16_bf16 v[80:95], v[80:83], v[104:107], 0
	s_waitcnt lgkmcnt(0)
	v_mfma_f32_32x32x16_bf16 v[80:95], v[64:67], v[108:111], v[80:95]
	ds_read_b128 v[64:67], v217 offset:4096
	s_waitcnt lgkmcnt(0)
	v_mfma_f32_32x32x16_bf16 v[64:79], v[64:67], v[104:107], 0
	v_add_f32_e32 v182, v182, v204
	v_add_f32_e32 v183, v183, v205
	v_add_f32_e32 v182, v182, v202
	v_add_f32_e32 v183, v183, v203
	v_add_f32_e32 v182, v182, v200
	v_add_f32_e32 v183, v183, v201
	v_add_f32_e32 v182, v182, v206
	v_add_f32_e32 v183, v183, v207
	v_add_f32_e32 v182, v182, v214
	v_add_f32_e32 v183, v183, v215
	v_add_f32_e32 v182, v182, v212
	v_add_f32_e32 v183, v183, v213
	v_add_f32_e32 v182, v182, v208
	v_add_f32_e32 v183, v183, v209
	v_add_f32_e32 v182, v182, v210
	v_add_f32_e32 v183, v183, v211
	v_exp_f32_e32 v218, v80
	v_exp_f32_e32 v219, v81
	v_exp_f32_e32 v216, v82
	v_exp_f32_e32 v217, v83
	v_exp_f32_e32 v82, v84
	v_exp_f32_e32 v83, v85
	v_exp_f32_e32 v80, v86
	v_exp_f32_e32 v81, v87
	v_cvt_pk_bf16_f32 v230, v218, v219
	v_cvt_pk_bf16_f32 v231, v216, v217
	v_cvt_pk_bf16_f32 v232, v82, v83
	v_cvt_pk_bf16_f32 v233, v80, v81
	v_exp_f32_e32 v86, v92
	v_mfma_f32_32x32x16_bf16 v[32:47], v[128:131], v[230:233], v[32:47]
	v_exp_f32_e32 v128, v88
	v_exp_f32_e32 v129, v89
	v_exp_f32_e32 v88, v90
	v_exp_f32_e32 v89, v91
	v_exp_f32_e32 v87, v93
	v_exp_f32_e32 v84, v94
	v_exp_f32_e32 v85, v95
	v_mfma_f32_32x32x16_bf16 v[0:15], v[152:155], v[230:233], v[0:15]
	v_cvt_pk_bf16_f32 v90, v128, v129
	v_cvt_pk_bf16_f32 v91, v88, v89
	v_cvt_pk_bf16_f32 v92, v86, v87
	v_cvt_pk_bf16_f32 v93, v84, v85
	s_nop 0
	v_mfma_f32_32x32x16_bf16 v[32:47], v[144:147], v[90:93], v[32:47]
	v_mfma_f32_32x32x16_bf16 v[0:15], v[156:159], v[90:93], v[0:15]
	ds_read_b128 v[90:93], v220 offset:4096
	s_waitcnt lgkmcnt(0)
	v_mfma_f32_32x32x16_bf16 v[64:79], v[90:93], v[108:111], v[64:79]
	v_add_f32_e32 v180, v180, v218
	v_add_f32_e32 v181, v181, v219
	v_add_f32_e32 v180, v180, v216
	v_add_f32_e32 v181, v181, v217
	v_add_f32_e32 v180, v180, v82
	v_add_f32_e32 v181, v181, v83
	v_add_f32_e32 v180, v180, v80
	v_add_f32_e32 v181, v181, v81
	v_add_f32_e32 v180, v180, v128
	v_add_f32_e32 v181, v181, v129
	v_add_f32_e32 v180, v180, v88
	v_add_f32_e32 v181, v181, v89
	v_add_f32_e32 v180, v180, v86
	v_add_f32_e32 v181, v181, v87
	v_add_f32_e32 v180, v180, v84
	v_add_f32_e32 v181, v181, v85
	v_exp_f32_e32 v92, v64
	v_exp_f32_e32 v93, v65
	v_exp_f32_e32 v90, v66
	v_exp_f32_e32 v91, v67
	v_exp_f32_e32 v66, v68
	v_exp_f32_e32 v67, v69
	v_exp_f32_e32 v64, v70
	v_exp_f32_e32 v65, v71
	v_cvt_pk_bf16_f32 v144, v92, v93
	v_cvt_pk_bf16_f32 v145, v90, v91
	v_cvt_pk_bf16_f32 v146, v66, v67
	v_cvt_pk_bf16_f32 v147, v64, v65
	v_exp_f32_e32 v94, v72
	v_mfma_f32_32x32x16_bf16 v[32:47], v[140:143], v[144:147], v[32:47]
	v_exp_f32_e32 v95, v73
	v_exp_f32_e32 v72, v74
	v_exp_f32_e32 v73, v75
	v_exp_f32_e32 v68, v76
	v_exp_f32_e32 v69, v77
	v_exp_f32_e32 v70, v78
	v_exp_f32_e32 v71, v79
	v_mfma_f32_32x32x16_bf16 v[0:15], v[148:151], v[144:147], v[0:15]
	v_cvt_pk_bf16_f32 v74, v94, v95
	v_cvt_pk_bf16_f32 v75, v72, v73
	v_cvt_pk_bf16_f32 v76, v68, v69
	v_cvt_pk_bf16_f32 v77, v70, v71
	s_nop 0
	v_mfma_f32_32x32x16_bf16 v[32:47], v[132:135], v[74:77], v[32:47]
	v_mfma_f32_32x32x16_bf16 v[0:15], v[136:139], v[74:77], v[0:15]
	s_cbranch_vccnz .LBB0_170
	s_xor_b32 s22, s25, 1
	v_lshl_add_u32 v75, s22, 13, v243
	v_lshl_add_u32 v74, s22, 13, v248
	s_mulk_i32 s22, 0x2200
	s_waitcnt vmcnt(3)
	ds_write_b128 v74, v[112:115]
	s_waitcnt vmcnt(2)
	ds_write_b128 v75, v[116:119]
	v_add_u32_e32 v75, s22, v249
	s_waitcnt vmcnt(0)
	ds_write2_b64 v75, v[120:121], v[122:123] offset1:1
	ds_write2_b64 v75, v[124:125], v[126:127] offset0:2 offset1:3
	s_branch .LBB0_170

; DEVI void scan_item(const Params& p, int l, int item, unsigned char* smem) {
;     ...
;   const int tl = tid >> 4, cg4 = (tid & 15) * 4;
;   const f32x4 kkc = *(const f32x4*)(p.k_k + l * 512 + h * 64 + cg4);
;   const f32x4 kac = *(const f32x4*)(p.k_a + l * 512 + h * 64 + cg4);
;   ScRaw RA, RB;
;   RA.gv[0] = 0; RA.gv[1] = 0; RB.gv[0] = 0; RB.gv[1] = 0;
;     ...
;   SC_LOAD(0, RA);
;   SC_LOAD(1, RB);
;   SC_STAGE(0, RA);
;   __syncthreads();
;   f32x2 S01 = {0.f, 0.f}, S23 = {0.f, 0.f};
;   const int vidx = 320 + wave * 4 + rl;
;   const bool bit3 = (kl & 8) != 0, bit2 = (kl & 4) != 0, bit1 = (kl & 2) != 0, bit0 = (kl & 1) != 0;
;   __builtin_amdgcn_s_setprio(3);
.LBB0_190:
	s_or_b64 exec, exec, s[42:43]
	v_ashrrev_i32_e32 v9, 31, v8
	v_lshlrev_b64 v[10:11], 10, v[8:9]
	v_lshl_add_u64 v[18:19], s[30:31], 0, v[10:11]
	v_lshl_add_u64 v[18:19], v[18:19], 0, s[96:97]
	v_lshl_add_u64 v[10:11], s[22:23], 0, v[10:11]
	v_lshl_or_b32 v8, v8, 3, s24
	v_readlane_b32 s42, v253, 24
	v_lshl_add_u64 v[18:19], v[18:19], 0, v[162:163]
	v_lshl_add_u64 v[10:11], v[10:11], 0, s[96:97]
	v_ashrrev_i32_e32 v9, 31, v8
	v_readlane_b32 s43, v253, 25
	v_lshl_add_u64 v[10:11], v[10:11], 0, v[162:163]
	s_waitcnt vmcnt(4)
	v_cvt_f32_f16_e32 v24, v75
	v_lshl_add_u64 v[8:9], v[8:9], 2, s[42:43]
	global_load_dwordx2 v[86:87], v[18:19], off
	global_load_dwordx2 v[88:89], v[10:11], off
	global_load_dword v90, v[8:9], off
	v_cvt_f32_f16_e32 v18, v74
	v_cvt_f32_f16_sdwa v19, v74 dst_sel:DWORD dst_unused:UNUSED_PAD src0_sel:WORD_1
	v_cvt_f32_f16_sdwa v25, v75 dst_sel:DWORD dst_unused:UNUSED_PAD src0_sel:WORD_1
	v_lshlrev_b32_e32 v30, 16, v72
	v_and_b32_e32 v31, 0xffff0000, v72
	s_waitcnt vmcnt(6)
	v_cvt_f32_f16_sdwa v33, v76 dst_sel:DWORD dst_unused:UNUSED_PAD src0_sel:WORD_1
	v_cvt_f32_f16_e32 v32, v76
	v_pk_mul_f32 v[20:21], v[0:1], v[30:31]
	v_cvt_f32_f16_sdwa v37, v77 dst_sel:DWORD dst_unused:UNUSED_PAD src0_sel:WORD_1
	v_cvt_f32_f16_e32 v36, v77
	v_mul_f32_e32 v18, 0x3fb8aa3b, v18
	v_mul_f32_e32 v19, 0x3fb8aa3b, v19
	s_waitcnt vmcnt(5)
	v_pk_mul_f32 v[22:23], v[20:21], v[78:79] op_sel_hi:[1,0]
	v_mul_f32_e32 v20, 0x3fb8aa3b, v24
	v_mul_f32_e32 v21, 0x3fb8aa3b, v25
	v_lshlrev_b32_e32 v34, 16, v73
	v_and_b32_e32 v35, 0xffff0000, v73
	v_exp_f32_e32 v18, v18
	v_exp_f32_e32 v19, v19
	v_exp_f32_e32 v20, v20
	v_exp_f32_e32 v21, v21
	v_pk_mul_f32 v[24:25], v[2:3], v[34:35]
	s_movk_i32 s2, 0x540
	v_pk_mul_f32 v[24:25], v[24:25], v[78:79] op_sel_hi:[1,0]
	v_mul_lo_u32 v17, v13, s2
	v_pk_mul_f32 v[28:29], v[36:37], v[24:25] neg_lo:[0,1] neg_hi:[0,1]
	v_pk_mul_f32 v[26:27], v[32:33], v[22:23] neg_lo:[0,1] neg_hi:[0,1]
	v_pk_add_f32 v[32:33], v[32:33], -1.0 op_sel_hi:[1,0]
	v_pk_add_f32 v[36:37], v[36:37], -1.0 op_sel_hi:[1,0]
	v_pk_fma_f32 v[38:39], v[4:5], v[32:33], 1.0 op_sel_hi:[1,1,0]
	v_pk_fma_f32 v[36:37], v[6:7], v[36:37], 1.0 op_sel_hi:[1,1,0]
	v_lshl_add_u32 v79, v15, 2, v17
	v_lshlrev_b32_e32 v8, 16, v70
	v_and_b32_e32 v9, 0xffff0000, v70
	v_lshlrev_b32_e32 v10, 16, v71
	v_and_b32_e32 v11, 0xffff0000, v71
	v_pk_mul_f32 v[32:33], v[36:37], v[34:35]
	v_pk_mul_f32 v[30:31], v[38:39], v[30:31]
	ds_write_b128 v79, v[18:21]
	ds_write_b128 v79, v[22:25] offset:256
	ds_write_b128 v79, v[26:29] offset:512
	ds_write_b128 v79, v[30:33] offset:768
	ds_write_b128 v79, v[8:11] offset:1024
	s_and_saveexec_b64 s[42:43], s[40:41]
	v_lshlrev_b32_e32 v8, 16, v68
	v_and_b32_e32 v9, 0xffff0000, v68
	v_lshlrev_b32_e32 v10, 16, v69
	v_and_b32_e32 v11, 0xffff0000, v69
	ds_write_b128 v79, v[8:11] offset:1280
	s_or_b64 exec, exec, s[42:43]
	v_and_b32_e32 v11, 8, v14
	v_cmp_eq_u32_e64 s[42:43], 0, v11
	v_and_b32_e32 v11, 4, v14
	v_cmp_eq_u32_e64 s[44:45], 0, v11
	v_and_b32_e32 v11, 2, v14
	v_cmp_eq_u32_e64 s[46:47], 0, v11
	v_and_b32_e32 v11, 1, v14
	v_lshrrev_b32_e32 v8, 4, v14
	v_bfe_u32 v9, v14, 4, 2
	s_add_u32 s37, s28, s25
	v_and_b32_e32 v10, -4, v13
	s_mov_b32 s25, 0
	v_cmp_eq_u32_e64 s[48:49], 0, v11
	s_addc_u32 s50, s29, 0
	s_waitcnt lgkmcnt(0)
	s_barrier
	s_setprio 3
	s_add_u32 s30, s30, s96
	s_addc_u32 s31, s31, 0
	v_lshlrev_b32_e32 v96, 2, v15
	v_bfi_b32 v8, -4, v13, v8
	s_add_u32 s22, s22, s96
	v_lshlrev_b32_e32 v91, 2, v8
	v_mad_u32_u24 v11, v12, 48, v96
	v_lshlrev_b32_e32 v8, 2, v10
	v_lshlrev_b32_e32 v9, 2, v9
	s_addc_u32 s23, s23, 0
	v_add3_u32 v97, v11, v8, v9
	v_lshl_add_u64 v[94:95], s[22:23], 0, v[162:163]
	v_mad_u64_u32 v[98:99], s[22:23], v16, s2, v[96:97]
	s_lshl_b32 s26, s27, 4
	s_add_u32 s22, s37, s96
	s_addc_u32 s23, s50, 0
	s_lshl_b32 s27, s27, 5
	s_add_u32 s22, s22, s27
	s_addc_u32 s23, s23, 0
	v_lshlrev_b32_e32 v8, 1, v12
	v_mov_b32_e32 v9, v163
	s_lshl_b32 s27, s36, 13
	s_lshl_b32 s36, s36, 8
	v_lshl_add_u64 v[100:101], s[22:23], 0, v[8:9]
	s_bitset1_b32 s36, 15
	v_readlane_b32 s22, v253, 7
	s_movk_i32 s2, 0xffd0
	v_readlane_b32 s23, v253, 8
	s_add_u32 s22, s22, s96
	v_mov_b32_e32 v8, 0
	v_lshl_add_u64 v[92:93], s[30:31], 0, v[162:163]
	v_lshlrev_b32_e32 v99, 2, v14
	v_mad_i32_i24 v103, v12, s2, v11
	s_addc_u32 s23, s23, 0
	v_sub_u32_e32 v105, 0, v13
	v_add_u32_e32 v112, 48, v13
	v_mov_b32_e32 v9, v8
	v_mov_b32_e32 v10, v8
	v_mov_b32_e32 v11, v8
	s_branch .LBB0_195
	s_nop 0
	s_nop 0
	s_nop 0
	s_nop 0
	s_nop 0
	s_nop 0
	s_nop 0
	s_nop 0
	s_nop 0
	s_nop 0

.LBB0_205:
	ds_read_b128 v[12:15], v103 offset:21504
	ds_read_b128 v[16:19], v103 offset:21760
	ds_read_b128 v[20:23], v103 offset:22016
	ds_read_b128 v[24:27], v103 offset:22272
	ds_read_b128 v[28:31], v103 offset:22528
	ds_read_b32 v102, v91 offset:22784
	ds_read_b128 v[32:35], v103 offset:22848
	ds_read_b128 v[36:39], v103 offset:23104
	ds_read_b128 v[40:43], v103 offset:23360
	ds_read_b128 v[44:47], v103 offset:23616
	ds_read_b128 v[48:51], v103 offset:23872
	ds_read_b32 v104, v91 offset:24128
	ds_read_b128 v[52:55], v103 offset:24192
	ds_read_b128 v[56:59], v103 offset:24448
	ds_read_b128 v[60:63], v103 offset:24704
	ds_read_b128 v[64:67], v103 offset:24960
	ds_read_b128 v[106:109], v103 offset:25216
	ds_read_b32 v110, v91 offset:25472
	s_waitcnt lgkmcnt(14)
	v_pk_mul_f32 v[16:17], v[8:9], v[16:17]
	s_and_b64 vcc, exec, s[50:51]
	v_pk_fma_f32 v[16:17], v[10:11], v[18:19], v[16:17]
	s_waitcnt lgkmcnt(12)
	v_pk_mul_f32 v[18:19], v[26:27], v[102:103] op_sel_hi:[1,0]
	v_add_f32_e32 v111, v16, v17
	v_pk_mul_f32 v[16:17], v[24:25], v[102:103] op_sel_hi:[1,0]
	v_pk_fma_f32 v[10:11], v[10:11], v[14:15], v[18:19]
	v_pk_fma_f32 v[8:9], v[8:9], v[12:13], v[16:17]
	v_add_f32_dpp v12, v111, v111 quad_perm:[1,0,3,2] row_mask:0xf bank_mask:0xf bound_ctrl:1
	s_nop 1
	v_add_f32_dpp v12, v12, v12 quad_perm:[2,3,0,1] row_mask:0xf bank_mask:0xf bound_ctrl:1
	s_nop 1
	v_add_f32_dpp v12, v12, v12 row_half_mirror row_mask:0xf bank_mask:0xf bound_ctrl:1
	s_nop 1
	v_add_f32_dpp v12, v12, v12 row_mirror row_mask:0xf bank_mask:0xf bound_ctrl:1
	v_pk_fma_f32 v[8:9], v[20:21], v[12:13], v[8:9] op_sel_hi:[1,0,1]
	v_pk_fma_f32 v[10:11], v[22:23], v[12:13], v[10:11] op_sel_hi:[1,0,1]
	v_pk_mul_f32 v[12:13], v[28:29], v[8:9]
	s_nop 0
	v_pk_fma_f32 v[12:13], v[30:31], v[10:11], v[12:13]
	ds_read_b128 v[28:31], v103 offset:25536
	ds_read_b128 v[116:119], v103 offset:25792
	ds_read_b128 v[120:123], v103 offset:26048
	ds_read_b128 v[124:127], v103 offset:26304
	ds_read_b128 v[128:131], v103 offset:26560
	ds_read_b32 v148, v91 offset:26816
	v_add_f32_e32 v113, v12, v13
	s_waitcnt lgkmcnt(14)
	v_pk_mul_f32 v[12:13], v[36:37], v[8:9]
	v_pk_mul_f32 v[8:9], v[32:33], v[8:9]
	v_pk_fma_f32 v[12:13], v[38:39], v[10:11], v[12:13]
	s_waitcnt lgkmcnt(12)
	v_pk_fma_f32 v[8:9], v[44:45], v[104:105], v[8:9] op_sel_hi:[1,0,1]
	v_add_f32_e32 v12, v12, v13
	v_pk_mul_f32 v[10:11], v[34:35], v[10:11]
	s_nop 0
	v_add_f32_dpp v12, v12, v12 quad_perm:[1,0,3,2] row_mask:0xf bank_mask:0xf bound_ctrl:1
	v_pk_fma_f32 v[10:11], v[46:47], v[104:105], v[10:11] op_sel_hi:[1,0,1]
	s_nop 0
	v_add_f32_dpp v12, v12, v12 quad_perm:[2,3,0,1] row_mask:0xf bank_mask:0xf bound_ctrl:1
	s_nop 1
	v_add_f32_dpp v12, v12, v12 row_half_mirror row_mask:0xf bank_mask:0xf bound_ctrl:1
	s_nop 1
	v_add_f32_dpp v12, v12, v12 row_mirror row_mask:0xf bank_mask:0xf bound_ctrl:1
	v_pk_fma_f32 v[8:9], v[40:41], v[12:13], v[8:9] op_sel_hi:[1,0,1]
	v_pk_fma_f32 v[10:11], v[42:43], v[12:13], v[10:11] op_sel_hi:[1,0,1]
	v_pk_mul_f32 v[12:13], v[48:49], v[8:9]
	s_nop 0
	v_pk_fma_f32 v[12:13], v[50:51], v[10:11], v[12:13]
	ds_read_b128 v[48:51], v103 offset:26880
	ds_read_b128 v[132:135], v103 offset:27136
	ds_read_b128 v[136:139], v103 offset:27392
	ds_read_b128 v[140:143], v103 offset:27648
	ds_read_b128 v[144:147], v103 offset:27904
	ds_read_b32 v150, v91 offset:28160
	v_add_f32_e32 v114, v12, v13
	s_waitcnt lgkmcnt(14)
	v_pk_mul_f32 v[12:13], v[56:57], v[8:9]
	v_pk_mul_f32 v[8:9], v[52:53], v[8:9]
	v_pk_fma_f32 v[12:13], v[58:59], v[10:11], v[12:13]
	s_waitcnt lgkmcnt(12)
	v_pk_fma_f32 v[8:9], v[64:65], v[110:111], v[8:9] op_sel_hi:[1,0,1]
	v_add_f32_e32 v12, v12, v13
	v_pk_mul_f32 v[10:11], v[54:55], v[10:11]
	s_nop 0
	v_add_f32_dpp v12, v12, v12 quad_perm:[1,0,3,2] row_mask:0xf bank_mask:0xf bound_ctrl:1
	v_pk_fma_f32 v[10:11], v[66:67], v[110:111], v[10:11] op_sel_hi:[1,0,1]
	s_nop 0
	v_add_f32_dpp v12, v12, v12 quad_perm:[2,3,0,1] row_mask:0xf bank_mask:0xf bound_ctrl:1
	s_nop 1
	v_add_f32_dpp v12, v12, v12 row_half_mirror row_mask:0xf bank_mask:0xf bound_ctrl:1
	s_nop 1
	v_add_f32_dpp v12, v12, v12 row_mirror row_mask:0xf bank_mask:0xf bound_ctrl:1
	v_pk_fma_f32 v[32:33], v[60:61], v[12:13], v[8:9] op_sel_hi:[1,0,1]
	v_pk_fma_f32 v[34:35], v[62:63], v[12:13], v[10:11] op_sel_hi:[1,0,1]
	s_waitcnt lgkmcnt(10)
	v_pk_mul_f32 v[36:37], v[116:117], v[32:33]
	v_pk_mul_f32 v[8:9], v[106:107], v[32:33]
	v_pk_fma_f32 v[36:37], v[118:119], v[34:35], v[36:37]
	v_pk_mul_f32 v[28:29], v[28:29], v[32:33]
	v_add_f32_e32 v36, v36, v37
	s_waitcnt lgkmcnt(6)
	v_pk_fma_f32 v[28:29], v[124:125], v[148:149], v[28:29] op_sel_hi:[1,0,1]
	v_pk_mul_f32 v[30:31], v[30:31], v[34:35]
	v_add_f32_dpp v32, v36, v36 quad_perm:[1,0,3,2] row_mask:0xf bank_mask:0xf bound_ctrl:1
	v_pk_fma_f32 v[30:31], v[126:127], v[148:149], v[30:31] op_sel_hi:[1,0,1]
	v_pk_fma_f32 v[8:9], v[108:109], v[34:35], v[8:9]
	v_add_f32_dpp v32, v32, v32 quad_perm:[2,3,0,1] row_mask:0xf bank_mask:0xf bound_ctrl:1
	v_add_f32_e32 v115, v8, v9
	ds_read_b128 v[16:19], v103 offset:28224
	ds_read_b128 v[24:27], v103 offset:28480
	ds_read_b128 v[12:15], v103 offset:28736
	ds_read_b128 v[20:23], v103 offset:28992
	ds_read_b128 v[8:11], v103 offset:29248
	ds_read_b32 v102, v91 offset:29504
	v_add_f32_dpp v32, v32, v32 row_half_mirror row_mask:0xf bank_mask:0xf bound_ctrl:1
	s_nop 1
	v_add_f32_dpp v32, v32, v32 row_mirror row_mask:0xf bank_mask:0xf bound_ctrl:1
	v_pk_fma_f32 v[52:53], v[120:121], v[32:33], v[28:29] op_sel_hi:[1,0,1]
	v_pk_fma_f32 v[54:55], v[122:123], v[32:33], v[30:31] op_sel_hi:[1,0,1]
	s_waitcnt lgkmcnt(10)
	v_pk_mul_f32 v[56:57], v[132:133], v[52:53]
	v_pk_mul_f32 v[28:29], v[128:129], v[52:53]
	v_pk_fma_f32 v[56:57], v[134:135], v[54:55], v[56:57]
	v_pk_mul_f32 v[48:49], v[48:49], v[52:53]
	v_add_f32_e32 v56, v56, v57
	s_waitcnt lgkmcnt(6)
	v_pk_fma_f32 v[48:49], v[140:141], v[150:151], v[48:49] op_sel_hi:[1,0,1]
	v_pk_mul_f32 v[50:51], v[50:51], v[54:55]
	v_add_f32_dpp v52, v56, v56 quad_perm:[1,0,3,2] row_mask:0xf bank_mask:0xf bound_ctrl:1
	v_pk_fma_f32 v[50:51], v[142:143], v[150:151], v[50:51] op_sel_hi:[1,0,1]
	v_pk_fma_f32 v[28:29], v[130:131], v[54:55], v[28:29]
	v_add_f32_dpp v52, v52, v52 quad_perm:[2,3,0,1] row_mask:0xf bank_mask:0xf bound_ctrl:1
	v_add_f32_e32 v116, v28, v29
	ds_read_b128 v[36:39], v103 offset:29568
	ds_read_b128 v[44:47], v103 offset:29824
	ds_read_b128 v[32:35], v103 offset:30080
	ds_read_b128 v[40:43], v103 offset:30336
	ds_read_b128 v[28:31], v103 offset:30592
	ds_read_b32 v104, v91 offset:30848
	v_add_f32_dpp v52, v52, v52 row_half_mirror row_mask:0xf bank_mask:0xf bound_ctrl:1
	s_nop 1
	v_add_f32_dpp v52, v52, v52 row_mirror row_mask:0xf bank_mask:0xf bound_ctrl:1
	v_pk_fma_f32 v[110:111], v[136:137], v[52:53], v[48:49] op_sel_hi:[1,0,1]
	v_pk_fma_f32 v[108:109], v[138:139], v[52:53], v[50:51] op_sel_hi:[1,0,1]
	s_waitcnt lgkmcnt(10)
	v_pk_mul_f32 v[24:25], v[24:25], v[110:111]
	v_pk_mul_f32 v[16:17], v[16:17], v[110:111]
	v_pk_fma_f32 v[24:25], v[26:27], v[108:109], v[24:25]
	s_waitcnt lgkmcnt(6)
	v_pk_fma_f32 v[16:17], v[20:21], v[102:103], v[16:17] op_sel_hi:[1,0,1]
	v_add_f32_e32 v24, v24, v25
	v_pk_mul_f32 v[48:49], v[144:145], v[110:111]
	v_pk_mul_f32 v[18:19], v[18:19], v[108:109]
	v_add_f32_dpp v20, v24, v24 quad_perm:[1,0,3,2] row_mask:0xf bank_mask:0xf bound_ctrl:1
	v_pk_fma_f32 v[48:49], v[146:147], v[108:109], v[48:49]
	v_pk_fma_f32 v[18:19], v[22:23], v[102:103], v[18:19] op_sel_hi:[1,0,1]
	v_add_f32_dpp v20, v20, v20 quad_perm:[2,3,0,1] row_mask:0xf bank_mask:0xf bound_ctrl:1
	v_add_f32_e32 v117, v48, v49
	ds_read_b128 v[56:59], v103 offset:30912
	ds_read_b128 v[64:67], v103 offset:31168
	ds_read_b128 v[52:55], v103 offset:31424
	ds_read_b128 v[60:63], v103 offset:31680
	ds_read_b128 v[48:51], v103 offset:31936
	ds_read_b32 v106, v91 offset:32192
	v_add_f32_dpp v20, v20, v20 row_half_mirror row_mask:0xf bank_mask:0xf bound_ctrl:1
	s_nop 1
	v_add_f32_dpp v20, v20, v20 row_mirror row_mask:0xf bank_mask:0xf bound_ctrl:1
	v_pk_fma_f32 v[108:109], v[12:13], v[20:21], v[16:17] op_sel_hi:[1,0,1]
	v_pk_fma_f32 v[118:119], v[14:15], v[20:21], v[18:19] op_sel_hi:[1,0,1]
	s_waitcnt lgkmcnt(10)
	v_pk_mul_f32 v[44:45], v[44:45], v[108:109]
	v_pk_mul_f32 v[36:37], v[36:37], v[108:109]
	v_pk_fma_f32 v[44:45], v[46:47], v[118:119], v[44:45]
	s_waitcnt lgkmcnt(6)
	v_pk_fma_f32 v[36:37], v[40:41], v[104:105], v[36:37] op_sel_hi:[1,0,1]
	v_add_f32_e32 v44, v44, v45
	v_pk_mul_f32 v[38:39], v[38:39], v[118:119]
	v_pk_mul_f32 v[8:9], v[8:9], v[108:109]
	v_add_f32_dpp v40, v44, v44 quad_perm:[1,0,3,2] row_mask:0xf bank_mask:0xf bound_ctrl:1
	v_pk_fma_f32 v[38:39], v[42:43], v[104:105], v[38:39] op_sel_hi:[1,0,1]
	v_pk_fma_f32 v[8:9], v[10:11], v[118:119], v[8:9]
	v_add_f32_dpp v40, v40, v40 quad_perm:[2,3,0,1] row_mask:0xf bank_mask:0xf bound_ctrl:1
	v_add_f32_e32 v111, v8, v9
	ds_read_b128 v[8:11], v103 offset:32256
	ds_read_b128 v[12:15], v103 offset:32512
	ds_read_b128 v[16:19], v103 offset:32768
	ds_read_b128 v[20:23], v103 offset:33024
	ds_read_b128 v[24:27], v103 offset:33280
	ds_read_b32 v102, v91 offset:33536
	v_add_f32_dpp v40, v40, v40 row_half_mirror row_mask:0xf bank_mask:0xf bound_ctrl:1
	s_nop 1
	v_add_f32_dpp v40, v40, v40 row_mirror row_mask:0xf bank_mask:0xf bound_ctrl:1
	v_pk_fma_f32 v[108:109], v[32:33], v[40:41], v[36:37] op_sel_hi:[1,0,1]
	v_pk_fma_f32 v[120:121], v[34:35], v[40:41], v[38:39] op_sel_hi:[1,0,1]
	s_waitcnt lgkmcnt(10)
	v_pk_mul_f32 v[64:65], v[64:65], v[108:109]
	v_pk_mul_f32 v[56:57], v[56:57], v[108:109]
	v_pk_fma_f32 v[64:65], v[66:67], v[120:121], v[64:65]
	s_waitcnt lgkmcnt(6)
	v_pk_fma_f32 v[56:57], v[60:61], v[106:107], v[56:57] op_sel_hi:[1,0,1]
	v_add_f32_e32 v64, v64, v65
	v_pk_mul_f32 v[58:59], v[58:59], v[120:121]
	v_pk_mul_f32 v[28:29], v[28:29], v[108:109]
	v_add_f32_dpp v60, v64, v64 quad_perm:[1,0,3,2] row_mask:0xf bank_mask:0xf bound_ctrl:1
	v_pk_fma_f32 v[58:59], v[62:63], v[106:107], v[58:59] op_sel_hi:[1,0,1]
	v_pk_fma_f32 v[28:29], v[30:31], v[120:121], v[28:29]
	v_add_f32_dpp v60, v60, v60 quad_perm:[2,3,0,1] row_mask:0xf bank_mask:0xf bound_ctrl:1
	v_add_f32_e32 v118, v28, v29
	ds_read_b128 v[28:31], v103 offset:33600
	ds_read_b128 v[32:35], v103 offset:33856
	ds_read_b128 v[36:39], v103 offset:34112
	ds_read_b128 v[40:43], v103 offset:34368
	ds_read_b128 v[44:47], v103 offset:34624
	ds_read_b32 v104, v91 offset:34880
	v_add_f32_dpp v60, v60, v60 row_half_mirror row_mask:0xf bank_mask:0xf bound_ctrl:1
	s_nop 1
	v_add_f32_dpp v60, v60, v60 row_mirror row_mask:0xf bank_mask:0xf bound_ctrl:1
	v_pk_fma_f32 v[106:107], v[52:53], v[60:61], v[56:57] op_sel_hi:[1,0,1]
	v_pk_fma_f32 v[108:109], v[54:55], v[60:61], v[58:59] op_sel_hi:[1,0,1]
	s_waitcnt lgkmcnt(10)
	v_pk_mul_f32 v[12:13], v[12:13], v[106:107]
	v_pk_mul_f32 v[8:9], v[8:9], v[106:107]
	v_pk_fma_f32 v[12:13], v[14:15], v[108:109], v[12:13]
	s_waitcnt lgkmcnt(6)
	v_pk_fma_f32 v[8:9], v[20:21], v[102:103], v[8:9] op_sel_hi:[1,0,1]
	v_add_f32_e32 v12, v12, v13
	v_pk_mul_f32 v[10:11], v[10:11], v[108:109]
	v_pk_mul_f32 v[48:49], v[48:49], v[106:107]
	v_add_f32_dpp v12, v12, v12 quad_perm:[1,0,3,2] row_mask:0xf bank_mask:0xf bound_ctrl:1
	v_pk_fma_f32 v[10:11], v[22:23], v[102:103], v[10:11] op_sel_hi:[1,0,1]
	v_pk_fma_f32 v[48:49], v[50:51], v[108:109], v[48:49]
	v_add_f32_dpp v12, v12, v12 quad_perm:[2,3,0,1] row_mask:0xf bank_mask:0xf bound_ctrl:1
	v_add_f32_e32 v119, v48, v49
	ds_read_b128 v[48:51], v103 offset:34944
	ds_read_b128 v[52:55], v103 offset:35200
	ds_read_b128 v[56:59], v103 offset:35456
	ds_read_b128 v[60:63], v103 offset:35712
	ds_read_b128 v[64:67], v103 offset:35968
	ds_read_b32 v110, v91 offset:36224
	v_add_f32_dpp v12, v12, v12 row_half_mirror row_mask:0xf bank_mask:0xf bound_ctrl:1
	ds_read_b128 v[106:109], v103 offset:36288
	ds_read_b128 v[124:127], v103 offset:36544
	ds_read_b128 v[128:131], v103 offset:36800
	ds_read_b128 v[132:135], v103 offset:37056
	ds_read_b128 v[136:139], v103 offset:37312
	ds_read_b32 v170, v91 offset:37568
	v_add_f32_dpp v12, v12, v12 row_mirror row_mask:0xf bank_mask:0xf bound_ctrl:1
	v_pk_fma_f32 v[8:9], v[16:17], v[12:13], v[8:9] op_sel_hi:[1,0,1]
	v_pk_fma_f32 v[10:11], v[18:19], v[12:13], v[10:11] op_sel_hi:[1,0,1]
	v_pk_mul_f32 v[12:13], v[24:25], v[8:9]
	ds_read_b128 v[140:143], v103 offset:37632
	ds_read_b128 v[144:147], v103 offset:37888
	ds_read_b128 v[148:151], v103 offset:38144
	ds_read_b128 v[152:155], v103 offset:38400
	ds_read_b128 v[156:159], v103 offset:38656
	ds_read_b32 v172, v91 offset:38912
	v_pk_fma_f32 v[12:13], v[26:27], v[10:11], v[12:13]
	s_nop 0
	v_add_f32_e32 v120, v12, v13
	s_waitcnt lgkmcnt(14)
	v_pk_mul_f32 v[12:13], v[32:33], v[8:9]
	v_pk_mul_f32 v[8:9], v[28:29], v[8:9]
	v_pk_fma_f32 v[12:13], v[34:35], v[10:11], v[12:13]
	v_pk_fma_f32 v[8:9], v[40:41], v[104:105], v[8:9] op_sel_hi:[1,0,1]
	v_add_f32_e32 v12, v12, v13
	v_pk_mul_f32 v[10:11], v[30:31], v[10:11]
	s_nop 0
	v_add_f32_dpp v12, v12, v12 quad_perm:[1,0,3,2] row_mask:0xf bank_mask:0xf bound_ctrl:1
	v_pk_fma_f32 v[10:11], v[42:43], v[104:105], v[10:11] op_sel_hi:[1,0,1]
	s_nop 0
	v_add_f32_dpp v12, v12, v12 quad_perm:[2,3,0,1] row_mask:0xf bank_mask:0xf bound_ctrl:1
	s_nop 1
	v_add_f32_dpp v12, v12, v12 row_half_mirror row_mask:0xf bank_mask:0xf bound_ctrl:1
	s_nop 1
	v_add_f32_dpp v12, v12, v12 row_mirror row_mask:0xf bank_mask:0xf bound_ctrl:1
	v_pk_fma_f32 v[8:9], v[36:37], v[12:13], v[8:9] op_sel_hi:[1,0,1]
	v_pk_fma_f32 v[10:11], v[38:39], v[12:13], v[10:11] op_sel_hi:[1,0,1]
	v_pk_mul_f32 v[12:13], v[44:45], v[8:9]
	s_nop 0
	v_pk_fma_f32 v[12:13], v[46:47], v[10:11], v[12:13]
	s_nop 0
	v_add_f32_e32 v121, v12, v13
	v_pk_mul_f32 v[12:13], v[52:53], v[8:9]
	v_pk_mul_f32 v[8:9], v[48:49], v[8:9]
	v_pk_fma_f32 v[12:13], v[54:55], v[10:11], v[12:13]
	s_waitcnt lgkmcnt(12)
	v_pk_fma_f32 v[8:9], v[60:61], v[110:111], v[8:9] op_sel_hi:[1,0,1]
	v_add_f32_e32 v12, v12, v13
	v_pk_mul_f32 v[10:11], v[50:51], v[10:11]
	s_nop 0
	v_add_f32_dpp v12, v12, v12 quad_perm:[1,0,3,2] row_mask:0xf bank_mask:0xf bound_ctrl:1
	v_pk_fma_f32 v[10:11], v[62:63], v[110:111], v[10:11] op_sel_hi:[1,0,1]
	s_nop 0
	v_add_f32_dpp v12, v12, v12 quad_perm:[2,3,0,1] row_mask:0xf bank_mask:0xf bound_ctrl:1
	s_nop 1
	v_add_f32_dpp v12, v12, v12 row_half_mirror row_mask:0xf bank_mask:0xf bound_ctrl:1
	s_nop 1
	v_add_f32_dpp v12, v12, v12 row_mirror row_mask:0xf bank_mask:0xf bound_ctrl:1
	v_pk_fma_f32 v[28:29], v[56:57], v[12:13], v[8:9] op_sel_hi:[1,0,1]
	v_pk_fma_f32 v[30:31], v[58:59], v[12:13], v[10:11] op_sel_hi:[1,0,1]
	s_waitcnt lgkmcnt(10)
	v_pk_mul_f32 v[32:33], v[124:125], v[28:29]
	v_pk_mul_f32 v[8:9], v[64:65], v[28:29]
	v_pk_fma_f32 v[32:33], v[126:127], v[30:31], v[32:33]
	v_pk_mul_f32 v[28:29], v[106:107], v[28:29]
	v_add_f32_e32 v32, v32, v33
	v_pk_fma_f32 v[8:9], v[66:67], v[30:31], v[8:9]
	s_waitcnt lgkmcnt(6)
	v_pk_fma_f32 v[28:29], v[132:133], v[170:171], v[28:29] op_sel_hi:[1,0,1]
	v_add_f32_dpp v32, v32, v32 quad_perm:[1,0,3,2] row_mask:0xf bank_mask:0xf bound_ctrl:1
	v_pk_mul_f32 v[30:31], v[108:109], v[30:31]
	v_add_f32_e32 v122, v8, v9
	v_add_f32_dpp v32, v32, v32 quad_perm:[2,3,0,1] row_mask:0xf bank_mask:0xf bound_ctrl:1
	v_pk_fma_f32 v[30:31], v[134:135], v[170:171], v[30:31] op_sel_hi:[1,0,1]
	ds_read_b128 v[16:19], v103 offset:38976
	ds_read_b128 v[24:27], v103 offset:39232
	ds_read_b128 v[12:15], v103 offset:39488
	ds_read_b128 v[20:23], v103 offset:39744
	ds_read_b128 v[8:11], v103 offset:40000
	ds_read_b32 v102, v91 offset:40256
	v_add_f32_dpp v32, v32, v32 row_half_mirror row_mask:0xf bank_mask:0xf bound_ctrl:1
	s_nop 1
	v_add_f32_dpp v32, v32, v32 row_mirror row_mask:0xf bank_mask:0xf bound_ctrl:1
	v_pk_fma_f32 v[48:49], v[128:129], v[32:33], v[28:29] op_sel_hi:[1,0,1]
	v_pk_fma_f32 v[50:51], v[130:131], v[32:33], v[30:31] op_sel_hi:[1,0,1]
	s_waitcnt lgkmcnt(10)
	v_pk_mul_f32 v[52:53], v[144:145], v[48:49]
	v_pk_mul_f32 v[28:29], v[136:137], v[48:49]
	v_pk_fma_f32 v[52:53], v[146:147], v[50:51], v[52:53]
	v_pk_mul_f32 v[48:49], v[140:141], v[48:49]
	v_add_f32_e32 v52, v52, v53
	v_pk_fma_f32 v[28:29], v[138:139], v[50:51], v[28:29]
	s_waitcnt lgkmcnt(6)
	v_pk_fma_f32 v[48:49], v[152:153], v[172:173], v[48:49] op_sel_hi:[1,0,1]
	v_add_f32_dpp v52, v52, v52 quad_perm:[1,0,3,2] row_mask:0xf bank_mask:0xf bound_ctrl:1
	v_pk_mul_f32 v[50:51], v[142:143], v[50:51]
	v_add_f32_e32 v123, v28, v29
	v_add_f32_dpp v52, v52, v52 quad_perm:[2,3,0,1] row_mask:0xf bank_mask:0xf bound_ctrl:1
	v_pk_fma_f32 v[50:51], v[154:155], v[172:173], v[50:51] op_sel_hi:[1,0,1]
	ds_read_b128 v[36:39], v103 offset:40320
	ds_read_b128 v[44:47], v103 offset:40576
	ds_read_b128 v[32:35], v103 offset:40832
	ds_read_b128 v[40:43], v103 offset:41088
	ds_read_b128 v[28:31], v103 offset:41344
	ds_read_b32 v104, v91 offset:41600
	v_add_f32_dpp v52, v52, v52 row_half_mirror row_mask:0xf bank_mask:0xf bound_ctrl:1
	s_nop 1
	v_add_f32_dpp v52, v52, v52 row_mirror row_mask:0xf bank_mask:0xf bound_ctrl:1
	v_pk_fma_f32 v[108:109], v[148:149], v[52:53], v[48:49] op_sel_hi:[1,0,1]
	v_pk_fma_f32 v[106:107], v[150:151], v[52:53], v[50:51] op_sel_hi:[1,0,1]
	s_waitcnt lgkmcnt(10)
	v_pk_mul_f32 v[24:25], v[24:25], v[108:109]
	v_pk_mul_f32 v[16:17], v[16:17], v[108:109]
	v_pk_fma_f32 v[24:25], v[26:27], v[106:107], v[24:25]
	s_waitcnt lgkmcnt(6)
	v_pk_fma_f32 v[16:17], v[20:21], v[102:103], v[16:17] op_sel_hi:[1,0,1]
	v_add_f32_e32 v24, v24, v25
	v_pk_mul_f32 v[18:19], v[18:19], v[106:107]
	v_pk_mul_f32 v[48:49], v[156:157], v[108:109]
	v_add_f32_dpp v20, v24, v24 quad_perm:[1,0,3,2] row_mask:0xf bank_mask:0xf bound_ctrl:1
	v_pk_fma_f32 v[18:19], v[22:23], v[102:103], v[18:19] op_sel_hi:[1,0,1]
	v_pk_fma_f32 v[48:49], v[158:159], v[106:107], v[48:49]
	v_add_f32_dpp v20, v20, v20 quad_perm:[2,3,0,1] row_mask:0xf bank_mask:0xf bound_ctrl:1
	v_add_f32_e32 v124, v48, v49
	ds_read_b128 v[56:59], v103 offset:41664
	ds_read_b128 v[64:67], v103 offset:41920
	ds_read_b128 v[52:55], v103 offset:42176
	ds_read_b128 v[60:63], v103 offset:42432
	ds_read_b128 v[48:51], v103 offset:42688
	ds_read_b32 v110, v91 offset:42944
	v_add_f32_dpp v20, v20, v20 row_half_mirror row_mask:0xf bank_mask:0xf bound_ctrl:1
	s_nop 1
	v_add_f32_dpp v20, v20, v20 row_mirror row_mask:0xf bank_mask:0xf bound_ctrl:1
	v_pk_fma_f32 v[12:13], v[12:13], v[20:21], v[16:17] op_sel_hi:[1,0,1]
	v_pk_fma_f32 v[14:15], v[14:15], v[20:21], v[18:19] op_sel_hi:[1,0,1]
	v_pk_mul_f32 v[8:9], v[8:9], v[12:13]
	v_cndmask_b32_e64 v18, v115, v122, s[42:43]
	v_pk_fma_f32 v[8:9], v[10:11], v[14:15], v[8:9]
	s_waitcnt lgkmcnt(11)
	v_pk_mul_f32 v[10:11], v[38:39], v[14:15]
	v_add_f32_e32 v16, v8, v9
	s_waitcnt lgkmcnt(10)
	v_pk_mul_f32 v[8:9], v[44:45], v[12:13]
	s_waitcnt lgkmcnt(6)
	v_pk_fma_f32 v[10:11], v[42:43], v[104:105], v[10:11] op_sel_hi:[1,0,1]
	v_pk_fma_f32 v[8:9], v[46:47], v[14:15], v[8:9]
	v_cndmask_b32_e64 v15, v113, v120, s[42:43]
	v_add_f32_e32 v17, v8, v9
	v_pk_mul_f32 v[8:9], v[36:37], v[12:13]
	v_cndmask_b32_e64 v19, v116, v123, s[42:43]
	v_add_f32_dpp v12, v17, v17 quad_perm:[1,0,3,2] row_mask:0xf bank_mask:0xf bound_ctrl:1
	v_pk_fma_f32 v[8:9], v[40:41], v[104:105], v[8:9] op_sel_hi:[1,0,1]
	v_cndmask_b32_e64 v17, v114, v121, s[42:43]
	v_add_f32_dpp v12, v12, v12 quad_perm:[2,3,0,1] row_mask:0xf bank_mask:0xf bound_ctrl:1
	v_cndmask_b32_e64 v20, v117, v124, s[42:43]
	s_nop 0
	v_add_f32_dpp v12, v12, v12 row_half_mirror row_mask:0xf bank_mask:0xf bound_ctrl:1
	s_nop 1
	v_add_f32_dpp v12, v12, v12 row_mirror row_mask:0xf bank_mask:0xf bound_ctrl:1
	v_pk_fma_f32 v[8:9], v[32:33], v[12:13], v[8:9] op_sel_hi:[1,0,1]
	v_pk_fma_f32 v[10:11], v[34:35], v[12:13], v[10:11] op_sel_hi:[1,0,1]
	v_pk_mul_f32 v[12:13], v[28:29], v[8:9]
	s_nop 0
	v_pk_fma_f32 v[12:13], v[30:31], v[10:11], v[12:13]
	s_nop 0
	v_add_f32_e32 v14, v12, v13
	s_waitcnt lgkmcnt(4)
	v_pk_mul_f32 v[12:13], v[64:65], v[8:9]
	v_pk_mul_f32 v[8:9], v[56:57], v[8:9]
	v_pk_fma_f32 v[12:13], v[66:67], v[10:11], v[12:13]
	s_waitcnt lgkmcnt(0)
	v_pk_fma_f32 v[8:9], v[60:61], v[110:111], v[8:9] op_sel_hi:[1,0,1]
	v_add_f32_e32 v12, v12, v13
	v_pk_mul_f32 v[10:11], v[58:59], v[10:11]
	s_nop 0
	v_add_f32_dpp v12, v12, v12 quad_perm:[1,0,3,2] row_mask:0xf bank_mask:0xf bound_ctrl:1
	v_pk_fma_f32 v[10:11], v[62:63], v[110:111], v[10:11] op_sel_hi:[1,0,1]
	s_nop 0
	v_add_f32_dpp v12, v12, v12 quad_perm:[2,3,0,1] row_mask:0xf bank_mask:0xf bound_ctrl:1
	s_nop 1
	v_add_f32_dpp v12, v12, v12 row_half_mirror row_mask:0xf bank_mask:0xf bound_ctrl:1
	s_nop 1
	v_add_f32_dpp v12, v12, v12 row_mirror row_mask:0xf bank_mask:0xf bound_ctrl:1
	v_pk_fma_f32 v[8:9], v[52:53], v[12:13], v[8:9] op_sel_hi:[1,0,1]
	v_pk_fma_f32 v[10:11], v[54:55], v[12:13], v[10:11] op_sel_hi:[1,0,1]
	v_pk_mul_f32 v[12:13], v[48:49], v[8:9]
	s_nop 0
	v_pk_fma_f32 v[12:13], v[50:51], v[10:11], v[12:13]
	s_nop 0
	v_add_f32_e32 v12, v12, v13
	v_cndmask_b32_e64 v13, v120, v113, s[42:43]
	s_nop 1
	v_add_f32_dpp v13, v15, v13 row_ror:8 row_mask:0xf bank_mask:0xf bound_ctrl:1
	v_cndmask_b32_e64 v15, v121, v114, s[42:43]
	s_nop 1
	v_add_f32_dpp v15, v17, v15 row_ror:8 row_mask:0xf bank_mask:0xf bound_ctrl:1
	v_cndmask_b32_e64 v17, v122, v115, s[42:43]
	s_nop 1
	v_add_f32_dpp v17, v18, v17 row_ror:8 row_mask:0xf bank_mask:0xf bound_ctrl:1
	v_cndmask_b32_e64 v18, v123, v116, s[42:43]
	s_nop 1
	v_add_f32_dpp v18, v19, v18 row_ror:8 row_mask:0xf bank_mask:0xf bound_ctrl:1
	v_cndmask_b32_e64 v19, v124, v117, s[42:43]
	s_nop 1
	v_add_f32_dpp v19, v20, v19 row_ror:8 row_mask:0xf bank_mask:0xf bound_ctrl:1
	v_cndmask_b32_e64 v20, v16, v111, s[42:43]
	v_cndmask_b32_e64 v16, v111, v16, s[42:43]
	s_nop 1
	v_add_f32_dpp v16, v16, v20 row_ror:8 row_mask:0xf bank_mask:0xf bound_ctrl:1
	v_cndmask_b32_e64 v20, v14, v118, s[42:43]
	v_cndmask_b32_e64 v14, v118, v14, s[42:43]
	s_nop 1
	v_add_f32_dpp v14, v14, v20 row_ror:8 row_mask:0xf bank_mask:0xf bound_ctrl:1
	v_cndmask_b32_e64 v20, v12, v119, s[42:43]
	v_cndmask_b32_e64 v12, v119, v12, s[42:43]
	s_nop 1
	v_add_f32_dpp v12, v12, v20 row_ror:8 row_mask:0xf bank_mask:0xf bound_ctrl:1
	v_cndmask_b32_e64 v20, v19, v13, s[44:45]
	v_cndmask_b32_e64 v13, v13, v19, s[44:45]
	v_cndmask_b32_e64 v19, v16, v15, s[44:45]
	v_cndmask_b32_e64 v15, v15, v16, s[44:45]
	v_cndmask_b32_e64 v16, v14, v17, s[44:45]
	v_cndmask_b32_e64 v14, v17, v14, s[44:45]
	v_add_f32_dpp v13, v13, v20 row_half_mirror row_mask:0xf bank_mask:0xf bound_ctrl:1
	v_add_f32_dpp v15, v15, v19 row_half_mirror row_mask:0xf bank_mask:0xf bound_ctrl:1
	v_add_f32_dpp v14, v14, v16 row_half_mirror row_mask:0xf bank_mask:0xf bound_ctrl:1
	v_cndmask_b32_e64 v16, v12, v18, s[44:45]
	v_cndmask_b32_e64 v12, v18, v12, s[44:45]
	s_nop 1
	v_add_f32_dpp v12, v12, v16 row_half_mirror row_mask:0xf bank_mask:0xf bound_ctrl:1
	v_cndmask_b32_e64 v16, v14, v13, s[46:47]
	v_cndmask_b32_e64 v13, v13, v14, s[46:47]
	v_cndmask_b32_e64 v14, v12, v15, s[46:47]
	v_cndmask_b32_e64 v12, v15, v12, s[46:47]
	v_add_f32_dpp v13, v13, v16 quad_perm:[2,3,0,1] row_mask:0xf bank_mask:0xf bound_ctrl:1
	s_nop 0
	v_add_f32_dpp v12, v12, v14 quad_perm:[2,3,0,1] row_mask:0xf bank_mask:0xf bound_ctrl:1
	v_cndmask_b32_e64 v14, v12, v13, s[48:49]
	v_cndmask_b32_e64 v12, v13, v12, s[48:49]
	s_nop 1
	v_add_f32_dpp v12, v12, v14 quad_perm:[1,0,3,2] row_mask:0xf bank_mask:0xf bound_ctrl:1
	ds_write_b32 v97, v12 offset:44032
	s_cbranch_vccnz .LBB0_194
	v_cvt_f32_f16_e32 v16, v74
	v_cvt_f32_f16_sdwa v17, v74 dst_sel:DWORD dst_unused:UNUSED_PAD src0_sel:WORD_1
	v_cvt_f32_f16_e32 v22, v75
	v_cvt_f32_f16_sdwa v23, v75 dst_sel:DWORD dst_unused:UNUSED_PAD src0_sel:WORD_1
	v_lshlrev_b32_e32 v28, 16, v72
	v_and_b32_e32 v29, 0xffff0000, v72
	v_cvt_f32_f16_sdwa v31, v76 dst_sel:DWORD dst_unused:UNUSED_PAD src0_sel:WORD_1
	v_cvt_f32_f16_e32 v30, v76
	v_pk_mul_f32 v[18:19], v[0:1], v[28:29]
	v_cvt_f32_f16_sdwa v35, v77 dst_sel:DWORD dst_unused:UNUSED_PAD src0_sel:WORD_1
	v_cvt_f32_f16_e32 v34, v77
	v_mul_f32_e32 v16, 0x3fb8aa3b, v16
	v_mul_f32_e32 v17, 0x3fb8aa3b, v17
	v_pk_mul_f32 v[20:21], v[78:79], v[18:19] op_sel_hi:[0,1]
	v_mul_f32_e32 v18, 0x3fb8aa3b, v22
	v_mul_f32_e32 v19, 0x3fb8aa3b, v23
	v_lshlrev_b32_e32 v32, 16, v73
	v_and_b32_e32 v33, 0xffff0000, v73
	v_exp_f32_e32 v16, v16
	v_exp_f32_e32 v17, v17
	v_exp_f32_e32 v18, v18
	v_exp_f32_e32 v19, v19
	v_pk_mul_f32 v[22:23], v[2:3], v[32:33]
	v_pk_mul_f32 v[24:25], v[30:31], v[20:21] neg_lo:[0,1] neg_hi:[0,1]
	v_pk_mul_f32 v[22:23], v[78:79], v[22:23] op_sel_hi:[0,1]
	v_pk_mul_f32 v[26:27], v[34:35], v[22:23] neg_lo:[0,1] neg_hi:[0,1]
	v_pk_add_f32 v[30:31], v[30:31], -1.0 op_sel_hi:[1,0]
	v_pk_add_f32 v[34:35], v[34:35], -1.0 op_sel_hi:[1,0]
	v_pk_fma_f32 v[36:37], v[4:5], v[30:31], 1.0 op_sel_hi:[1,1,0]
	v_pk_fma_f32 v[34:35], v[6:7], v[34:35], 1.0 op_sel_hi:[1,1,0]
	v_lshlrev_b32_e32 v12, 16, v70
	v_and_b32_e32 v13, 0xffff0000, v70
	v_lshlrev_b32_e32 v14, 16, v71
	v_and_b32_e32 v15, 0xffff0000, v71
	v_pk_mul_f32 v[30:31], v[34:35], v[32:33]
	v_pk_mul_f32 v[28:29], v[36:37], v[28:29]
	ds_write_b128 v79, v[16:19]
	ds_write_b128 v79, v[20:23] offset:256
	ds_write_b128 v79, v[24:27] offset:512
	ds_write_b128 v79, v[28:31] offset:768
	ds_write_b128 v79, v[12:15] offset:1024
	s_and_saveexec_b64 s[50:51], s[40:41]
	s_cbranch_execz .LBB0_193
	v_lshlrev_b32_e32 v12, 16, v68
	v_and_b32_e32 v13, 0xffff0000, v68
	v_lshlrev_b32_e32 v14, 16, v69
	v_and_b32_e32 v15, 0xffff0000, v69
	ds_write_b128 v79, v[12:15] offset:1280
	s_branch .LBB0_193
	s_nop 0
	s_nop 0
	s_nop 0
	s_nop 0
	s_nop 0
	s_nop 0
